# speedup vs baseline: 1.0244x; 1.0089x over previous
.LBB0_248:
	s_and_b32 s2, s19, 7
	v_mul_u32_u24_e32 v0, s2, v229
	s_ashr_i32 s2, s19, 3
	v_add_u32_e32 v0, s2, v0
	s_waitcnt lgkmcnt(0)
	v_sub_u32_e32 v3, 0, v0
	v_max_i32_e32 v3, v0, v3
	v_mul_hi_u32 v4, v3, v196
	v_mul_lo_u32 v5, v4, v227
	v_sub_u32_e32 v3, v3, v5
	v_add_u32_e32 v5, 1, v4
	v_cmp_ge_u32_e32 vcc, v3, v227
	v_ashrrev_i32_e32 v2, 31, v0
	s_add_i32 s19, s19, s3
	v_cndmask_b32_e32 v4, v4, v5, vcc
	v_sub_u32_e32 v5, v3, v227
	v_cndmask_b32_e32 v3, v3, v5, vcc
	v_add_u32_e32 v5, 1, v4
	v_cmp_ge_u32_e32 vcc, v3, v227
	s_and_b32 s2, s19, 7
	v_mov_b32_e32 v204, v190
	v_cndmask_b32_e32 v3, v4, v5, vcc
	v_xor_b32_e32 v3, v3, v2
	v_sub_u32_e32 v2, v3, v2
	v_mul_lo_u32 v3, v2, v227
	v_sub_u32_e32 v0, v0, v3
	v_mul_u32_u24_e32 v3, s2, v229
	s_ashr_i32 s2, s19, 3
	v_add_u32_e32 v3, s2, v3
	v_sub_u32_e32 v5, 0, v3
	v_max_i32_e32 v5, v3, v5
	v_mul_hi_u32 v6, v5, v196
	v_mul_lo_u32 v7, v6, v227
	v_sub_u32_e32 v5, v5, v7
	v_add_u32_e32 v7, 1, v6
	v_cmp_ge_u32_e32 vcc, v5, v227
	v_ashrrev_i32_e32 v4, 31, v3
	v_lshlrev_b32_e32 v2, 11, v2
	v_cndmask_b32_e32 v6, v6, v7, vcc
	v_sub_u32_e32 v7, v5, v227
	v_cndmask_b32_e32 v5, v5, v7, vcc
	v_add_u32_e32 v7, 1, v6
	v_cmp_ge_u32_e32 vcc, v5, v227
	s_movk_i32 s2, 0x700
	v_readfirstlane_b32 s30, v225
	v_cndmask_b32_e32 v5, v6, v7, vcc
	v_xor_b32_e32 v5, v5, v4
	v_sub_u32_e32 v4, v5, v4
	v_mul_lo_u32 v5, v4, v227
	v_sub_u32_e32 v3, v3, v5
	v_lshlrev_b32_e32 v5, 8, v0
	v_and_or_b32 v2, v5, s2, v2
	v_lshlrev_b32_e32 v6, 4, v204
	v_readfirstlane_b32 s60, v2
	v_bfe_i32 v2, v204, 27, 1
	v_lshrrev_b32_e32 v2, 22, v2
	v_add_u32_e32 v2, v6, v2
	v_lshlrev_b32_e32 v5, 8, v3
	v_lshlrev_b32_e32 v3, 5, v3
	v_and_b32_e32 v2, 0xfffffc00, v2
	v_lshlrev_b32_e32 v0, 5, v0
	v_and_b32_e32 v5, 0x700, v5
	v_cmp_lt_i32_e32 vcc, s19, v226
	v_and_b32_e32 v3, 0xffffff00, v3
	v_sub_u32_e32 v2, v6, v2
	v_and_b32_e32 v0, 0xffffff00, v0
	v_lshl_or_b32 v4, v4, 11, v5
	v_lshrrev_b32_e32 v9, 8, v3
	v_mov_b32_e32 v10, v9
	v_cmp_eq_u32_e64 s[8:9], 19, v9
	s_nop 1
	v_cndmask_b32_e64 v10, v10, 24, s[8:9]
	v_cmp_eq_u32_e64 s[8:9], 24, v9
	s_nop 1
	v_cndmask_b32_e64 v10, v10, 19, s[8:9]
	v_cmp_eq_u32_e64 s[8:9], 15, v9
	s_nop 1
	v_cndmask_b32_e64 v10, v10, 25, s[8:9]
	v_cmp_eq_u32_e64 s[8:9], 25, v9
	s_nop 1
	v_cndmask_b32_e64 v10, v10, 15, s[8:9]
	v_cmp_eq_u32_e64 s[8:9], 26, v9
	s_nop 1
	v_cndmask_b32_e64 v10, v10, 30, s[8:9]
	v_cmp_eq_u32_e64 s[8:9], 30, v9
	s_nop 1
	v_cndmask_b32_e64 v10, v10, 26, s[8:9]
	v_cmp_eq_u32_e64 s[8:9], 0, v224
	s_nop 1
	v_cndmask_b32_e64 v9, v9, v10, s[8:9]
	v_lshlrev_b32_e32 v3, 8, v9
	v_cndmask_b32_e32 v5, 0, v3, vcc
	v_lshrrev_b32_e32 v3, 4, v2
	v_lshrrev_b32_e32 v9, 8, v0
	v_mov_b32_e32 v10, v9
	v_cmp_eq_u32_e64 s[8:9], 19, v9
	s_nop 1
	v_cndmask_b32_e64 v10, v10, 24, s[8:9]
	v_cmp_eq_u32_e64 s[8:9], 24, v9
	s_nop 1
	v_cndmask_b32_e64 v10, v10, 19, s[8:9]
	v_cmp_eq_u32_e64 s[8:9], 15, v9
	s_nop 1
	v_cndmask_b32_e64 v10, v10, 25, s[8:9]
	v_cmp_eq_u32_e64 s[8:9], 25, v9
	s_nop 1
	v_cndmask_b32_e64 v10, v10, 15, s[8:9]
	v_cmp_eq_u32_e64 s[8:9], 26, v9
	s_nop 1
	v_cndmask_b32_e64 v10, v10, 30, s[8:9]
	v_cmp_eq_u32_e64 s[8:9], 30, v9
	s_nop 1
	v_cndmask_b32_e64 v10, v10, 26, s[8:9]
	v_cmp_eq_u32_e64 s[8:9], 0, v224
	s_nop 1
	v_cndmask_b32_e64 v9, v9, v10, s[8:9]
	v_lshlrev_b32_e32 v0, 8, v9
	s_nop 0
	v_readfirstlane_b32 s94, v0
	v_ashrrev_i32_e32 v0, 31, v204
	v_bitop3_b32 v2, v3, v2, 32 bitop3:0x6c
	v_lshrrev_b32_e32 v0, 26, v0
	v_ashrrev_i32_e32 v7, 31, v2
	v_add_u32_e32 v0, v204, v0
	v_lshrrev_b32_e32 v7, 26, v7
	v_ashrrev_i32_e32 v0, 6, v0
	v_add_u32_e32 v7, v2, v7
	v_lshlrev_b32_e32 v3, 3, v0
	v_ashrrev_i32_e32 v8, 6, v7
	v_and_b32_e32 v7, 0xc0, v7
	v_and_b32_e32 v3, 0x7ffffff0, v3
	v_lshlrev_b32_e32 v0, 5, v0
	v_sub_u32_e32 v2, v2, v7
	v_add_u32_e32 v3, v8, v3
	v_and_b32_e32 v0, 32, v0
	v_ashrrev_i16_sdwa v2, v197, sext(v2) dst_sel:DWORD dst_unused:UNUSED_PAD src0_sel:DWORD src1_sel:BYTE_0
	s_ashr_i32 s31, s30, 31
	v_bfe_i32 v7, v2, 0, 16
	v_mad_u64_u32 v[2:3], s[8:9], v3, s30, v[0:1]
	s_ashr_i32 s2, s60, 31
	s_lshl_b64 s[74:75], s[30:31], 1
	s_mul_i32 s2, s74, s2
	s_mul_hi_u32 s8, s74, s60
	s_add_i32 s2, s8, s2
	s_lshr_b64 s[8:9], s[30:31], 31
	s_mul_i32 s9, s8, s60
	v_readfirstlane_b32 s84, v194
	s_add_i32 s2, s2, s9
	s_mul_i32 s9, s74, s60
	v_readfirstlane_b32 s77, v195
	s_add_u32 s24, s84, s9
	s_addc_u32 s2, s77, s2
	s_ashr_i32 s95, s94, 31
	s_and_b32 s25, s2, 0xffff
	s_mul_i32 s2, s74, s95
	s_mul_hi_u32 s9, s74, s94
	s_add_i32 s2, s9, s2
	s_mul_i32 s8, s8, s94
	v_readfirstlane_b32 s76, v192
	s_add_i32 s2, s2, s8
	s_mul_i32 s8, s74, s94
	v_readfirstlane_b32 s83, v193
	s_add_u32 s44, s76, s8
	v_add_lshl_u32 v0, v2, v7, 1
	s_addc_u32 s2, s83, s2
	v_cndmask_b32_e64 v2, 0, 1, vcc
	s_and_b32 s45, s2, 0xffff
	v_readfirstlane_b32 s2, v2
	v_cndmask_b32_e64 v2, 0, 1, s[46:47]
	s_bitcmp1_b32 s2, 0
	v_readfirstlane_b32 s2, v2
	s_cselect_b64 s[28:29], -1, 0
	s_bitcmp1_b32 s2, 0
	v_cndmask_b32_e32 v4, 0, v4, vcc
	s_cselect_b64 s[46:47], -1, 0
	v_add_u32_e32 v232, 0, v6
	v_cmp_ge_i32_e64 s[6:7], s19, v226
	v_readfirstlane_b32 s97, v224
	v_readfirstlane_b32 s96, v228
	v_readfirstlane_b32 s13, v4
	v_readfirstlane_b32 s9, v5
	s_lshl_b32 s8, s30, 7
	s_and_b64 vcc, exec, s[46:47]
	v_add_u32_e32 v236, 0x10000, v232
	v_add_u32_e32 v235, 0x12000, v232
	v_add_u32_e32 v234, 0x2000, v232
	v_add_u32_e32 v233, 0x14000, v232
	v_add_u32_e32 v231, 0x16000, v232
	s_mul_i32 s85, s30, 0x180
	v_add_u32_e32 v230, 0x4000, v232
	v_add_u32_e32 v205, 0x6000, v232
	s_cbranch_vccnz .LBB0_250
	v_readfirstlane_b32 s2, v236
	s_mov_b32 s46, s26
	s_mov_b32 s47, s27
	s_mov_b32 m0, s2
	v_readfirstlane_b32 s2, v235
	buffer_load_dwordx4 v0, s[44:47], 0 offen lds
	s_mov_b32 m0, s2
	v_readfirstlane_b32 s2, v232
	buffer_load_dwordx4 v0, s[44:47], s8 offen lds
	s_mov_b32 m0, s2
	v_readfirstlane_b32 s2, v234
	buffer_load_dwordx4 v0, s[24:27], 0 offen lds
	s_mov_b32 m0, s2
	v_readfirstlane_b32 s33, v233
	buffer_load_dwordx4 v0, s[24:27], s8 offen lds
	s_lshl_b32 s2, s30, 8
	s_mov_b32 m0, s33
	v_readfirstlane_b32 s33, v231
	buffer_load_dwordx4 v0, s[44:47], s2 offen lds
	s_mov_b32 m0, s33
	v_readfirstlane_b32 s33, v230
	buffer_load_dwordx4 v0, s[44:47], s85 offen lds
	s_mov_b32 m0, s33
	s_nop 0
	buffer_load_dwordx4 v0, s[24:27], s2 offen lds
	v_readfirstlane_b32 s2, v205
	s_mov_b32 m0, s2
	s_nop 0
	buffer_load_dwordx4 v0, s[24:27], s85 offen lds
